# cross-tile prefetch also on the odin K-loop
# baseline (speedup 1.0000x reference)
.LBB0_1510:
	s_mul_hi_i32 s6, s74, 0x2aaaaaab
	s_lshr_b32 s7, s6, 31
	s_ashr_i32 s6, s6, 4
	s_add_i32 s6, s6, s7
	s_mul_i32 s7, s6, 0x60
	s_sub_i32 s7, s74, s7
	s_lshl_b32 s11, s7, 7
	s_lshl_b32 s10, s6, 7
	v_lshl_or_b32 v64, v183, 3, v191
	v_and_b32_e32 v65, 63, v64
	v_lshrrev_b32_e32 v66, 3, v65
	v_lshrrev_b32_e32 v67, 4, v65
	v_xor_b32_e32 v67, v67, v65
	v_and_b32_e32 v67, 7, v67
	v_lshlrev_b32_e32 v67, 4, v67
	s_movk_i32 s99, 0x800
	v_mad_u32_u24 v112, v66, s99, v67
	v_xor_b32_e32 v68, 64, v112
	v_add_u32_e32 v113, 0x3c00, v68
	v_add_u32_e32 v114, 0x7800, v112
	v_add_u32_e32 v115, 0xb400, v68
	v_add_u32_e32 v116, 0x10000, v112
	v_add_u32_e32 v117, 0x13c00, v68
	v_add_u32_e32 v118, 0x17800, v112
	v_add_u32_e32 v119, 0x1b400, v68
	v_and_b32_e32 v69, 31, v64
	v_bfe_u32 v70, v64, 5, 1
	v_bfe_u32 v71, v64, 1, 3
	v_xor_b32_e32 v71, v71, v70
	v_lshlrev_b32_e32 v71, 4, v71
	v_bfe_u32 v72, v64, 7, 1
	v_lshl_or_b32 v72, v72, 6, v69
	v_lshl_add_u32 v120, v72, 7, v71
	v_bfe_u32 v73, v64, 6, 1
	v_lshl_or_b32 v73, v73, 6, v69
	v_lshl_add_u32 v124, v73, 7, v71
	v_add_u32_e32 v124, 0x4000, v124
	v_xor_b32_e32 v121, 32, v120
	v_xor_b32_e32 v125, 32, v124
	v_xor_b32_e32 v122, 64, v120
	v_xor_b32_e32 v126, 64, v124
	v_xor_b32_e32 v123, 96, v120
	v_xor_b32_e32 v127, 96, v124
	v_lshrrev_b32_e32 v74, 6, v64
	s_nop 0
	v_readfirstlane_b32 s100, v74
	s_nop 3
	s_lshl_b32 s98, s100, 13
	s_mov_b32 s101, 0x2c40000
	s_mov_b32 s99, s10
	s_cmp_lt_u32 s100, 2
	s_cmov_b32 s101, 0xb171900
	s_cmov_b32 s99, s11
	s_and_b32 s100, s100, 1
	s_lshl_b32 s100, s100, 6
	s_add_u32 s99, s99, s100
	s_mul_i32 s99, s99, 0x800
	s_add_u32 s99, s99, s101
	s_add_u32 s6, s90, s99
	s_addc_u32 s7, s91, 0
	v_readlane_b32 s99, v251, 0
	s_cmp_lg_u32 s99, 0
	s_cbranch_scc1 .Lg4_pref
	s_add_u32 m0, s98, 0x0
	s_nop 0
	global_load_lds_dwordx4 v112, s[6:7] offset:0
	global_load_lds_dwordx4 v113, s[6:7] offset:1024
	global_load_lds_dwordx4 v114, s[6:7] offset:2048
	global_load_lds_dwordx4 v115, s[6:7] offset:3072
	s_add_u32 m0, s98, 0x1000
	s_nop 0
	global_load_lds_dwordx4 v116, s[6:7] offset:0
	global_load_lds_dwordx4 v117, s[6:7] offset:1024
	global_load_lds_dwordx4 v118, s[6:7] offset:2048
	global_load_lds_dwordx4 v119, s[6:7] offset:3072
	s_add_u32 s6, s6, 0x80
	s_addc_u32 s7, s7, 0
	s_add_u32 m0, s98, 0x8000
	s_nop 0
	global_load_lds_dwordx4 v112, s[6:7] offset:0
	global_load_lds_dwordx4 v113, s[6:7] offset:1024
	global_load_lds_dwordx4 v114, s[6:7] offset:2048
	global_load_lds_dwordx4 v115, s[6:7] offset:3072
	s_add_u32 m0, s98, 0x9000
	s_nop 0
	global_load_lds_dwordx4 v116, s[6:7] offset:0
	global_load_lds_dwordx4 v117, s[6:7] offset:1024
	global_load_lds_dwordx4 v118, s[6:7] offset:2048
	global_load_lds_dwordx4 v119, s[6:7] offset:3072
	s_add_u32 s6, s6, 0x80
	s_addc_u32 s7, s7, 0
	s_mov_b32 s101, 0
	s_branch .Lg4_prol
.Lg4_pref:
	s_add_u32 s6, s6, 0x100
	s_addc_u32 s7, s7, 0
	s_mov_b32 s101, 1
.Lg4_prol:
	v_mov_b32_e32 v48, 0
	v_mov_b32_e32 v49, 0
	v_mov_b32_e32 v50, 0
	v_mov_b32_e32 v51, 0
	v_mov_b32_e32 v52, 0
	v_mov_b32_e32 v53, 0
	v_mov_b32_e32 v54, 0
	v_mov_b32_e32 v55, 0
	v_mov_b32_e32 v56, 0
	v_mov_b32_e32 v57, 0
	v_mov_b32_e32 v58, 0
	v_mov_b32_e32 v59, 0
	v_mov_b32_e32 v60, 0
	v_mov_b32_e32 v61, 0
	v_mov_b32_e32 v62, 0
	v_mov_b32_e32 v63, 0
	v_mov_b32_e32 v16, 0
	v_mov_b32_e32 v17, 0
	v_mov_b32_e32 v18, 0
	v_mov_b32_e32 v19, 0
	v_mov_b32_e32 v20, 0
	v_mov_b32_e32 v21, 0
	v_mov_b32_e32 v22, 0
	v_mov_b32_e32 v23, 0
	v_mov_b32_e32 v24, 0
	v_mov_b32_e32 v25, 0
	v_mov_b32_e32 v26, 0
	v_mov_b32_e32 v27, 0
	v_mov_b32_e32 v28, 0
	v_mov_b32_e32 v29, 0
	v_mov_b32_e32 v30, 0
	v_mov_b32_e32 v31, 0
	v_mov_b32_e32 v32, 0
	v_mov_b32_e32 v33, 0
	v_mov_b32_e32 v34, 0
	v_mov_b32_e32 v35, 0
	v_mov_b32_e32 v36, 0
	v_mov_b32_e32 v37, 0
	v_mov_b32_e32 v38, 0
	v_mov_b32_e32 v39, 0
	v_mov_b32_e32 v40, 0
	v_mov_b32_e32 v41, 0
	v_mov_b32_e32 v42, 0
	v_mov_b32_e32 v43, 0
	v_mov_b32_e32 v44, 0
	v_mov_b32_e32 v45, 0
	v_mov_b32_e32 v46, 0
	v_mov_b32_e32 v47, 0
	v_mov_b32_e32 v0, 0
	v_mov_b32_e32 v1, 0
	v_mov_b32_e32 v2, 0
	v_mov_b32_e32 v3, 0
	v_mov_b32_e32 v4, 0
	v_mov_b32_e32 v5, 0
	v_mov_b32_e32 v6, 0
	v_mov_b32_e32 v7, 0
	v_mov_b32_e32 v8, 0
	v_mov_b32_e32 v9, 0
	v_mov_b32_e32 v10, 0
	v_mov_b32_e32 v11, 0
	v_mov_b32_e32 v12, 0
	v_mov_b32_e32 v13, 0
	v_mov_b32_e32 v14, 0
	v_mov_b32_e32 v15, 0
	s_movk_i32 s8, 7
	s_cmp_lg_u32 s101, 0
	s_cbranch_scc1 .Lg4_w0p
	s_waitcnt vmcnt(8)
	s_branch .Lg4_loop

.Lg4_loop:
	s_barrier
	ds_read_b128 v[64:67], v120 offset:0
	ds_read_b128 v[72:75], v124 offset:0
	ds_read_b128 v[76:79], v124 offset:4096
	ds_read_b128 v[68:71], v120 offset:4096
	ds_read_b128 v[80:83], v121 offset:0
	ds_read_b128 v[88:91], v125 offset:0
	ds_read_b128 v[92:95], v125 offset:4096
	ds_read_b128 v[84:87], v121 offset:4096
	s_waitcnt lgkmcnt(4)
	v_mfma_f32_32x32x16_bf16 v[48:63], v[64:67], v[72:75], v[48:63]
	ds_read_b128 v[96:99], v122 offset:0
	v_mfma_f32_32x32x16_bf16 v[16:31], v[64:67], v[76:79], v[16:31]
	ds_read_b128 v[104:107], v126 offset:0
	v_mfma_f32_32x32x16_bf16 v[32:47], v[68:71], v[72:75], v[32:47]
	ds_read_b128 v[108:111], v126 offset:4096
	v_mfma_f32_32x32x16_bf16 v[0:15], v[68:71], v[76:79], v[0:15]
	ds_read_b128 v[100:103], v122 offset:4096
	s_waitcnt lgkmcnt(4)
	v_mfma_f32_32x32x16_bf16 v[48:63], v[80:83], v[88:91], v[48:63]
	ds_read_b128 v[64:67], v123 offset:0
	v_mfma_f32_32x32x16_bf16 v[16:31], v[80:83], v[92:95], v[16:31]
	ds_read_b128 v[72:75], v127 offset:0
	v_mfma_f32_32x32x16_bf16 v[32:47], v[84:87], v[88:91], v[32:47]
	ds_read_b128 v[76:79], v127 offset:4096
	v_mfma_f32_32x32x16_bf16 v[0:15], v[84:87], v[92:95], v[0:15]
	ds_read_b128 v[68:71], v123 offset:4096
	s_waitcnt lgkmcnt(4)
	v_mfma_f32_32x32x16_bf16 v[48:63], v[96:99], v[104:107], v[48:63]
	v_mfma_f32_32x32x16_bf16 v[16:31], v[96:99], v[108:111], v[16:31]
	v_mfma_f32_32x32x16_bf16 v[32:47], v[100:103], v[104:107], v[32:47]
	v_mfma_f32_32x32x16_bf16 v[0:15], v[100:103], v[108:111], v[0:15]
	s_waitcnt lgkmcnt(0)
	v_mfma_f32_32x32x16_bf16 v[48:63], v[64:67], v[72:75], v[48:63]
	v_mfma_f32_32x32x16_bf16 v[16:31], v[64:67], v[76:79], v[16:31]
	v_mfma_f32_32x32x16_bf16 v[32:47], v[68:71], v[72:75], v[32:47]
	v_mfma_f32_32x32x16_bf16 v[0:15], v[68:71], v[76:79], v[0:15]
	s_barrier
	s_add_u32 m0, s98, 0x0
	s_nop 0
	global_load_lds_dwordx4 v112, s[6:7] offset:0
	global_load_lds_dwordx4 v113, s[6:7] offset:1024
	global_load_lds_dwordx4 v114, s[6:7] offset:2048
	global_load_lds_dwordx4 v115, s[6:7] offset:3072
	s_add_u32 m0, s98, 0x1000
	s_nop 0
	global_load_lds_dwordx4 v116, s[6:7] offset:0
	global_load_lds_dwordx4 v117, s[6:7] offset:1024
	global_load_lds_dwordx4 v118, s[6:7] offset:2048
	global_load_lds_dwordx4 v119, s[6:7] offset:3072
	s_add_u32 s6, s6, 0x80
	s_addc_u32 s7, s7, 0
	s_waitcnt vmcnt(8)
	s_barrier
	ds_read_b128 v[64:67], v120 offset:32768
	ds_read_b128 v[72:75], v124 offset:32768
	ds_read_b128 v[76:79], v124 offset:36864
	ds_read_b128 v[68:71], v120 offset:36864
	ds_read_b128 v[80:83], v121 offset:32768
	ds_read_b128 v[88:91], v125 offset:32768
	ds_read_b128 v[92:95], v125 offset:36864
	ds_read_b128 v[84:87], v121 offset:36864
	s_waitcnt lgkmcnt(4)
	v_mfma_f32_32x32x16_bf16 v[48:63], v[64:67], v[72:75], v[48:63]
	ds_read_b128 v[96:99], v122 offset:32768
	v_mfma_f32_32x32x16_bf16 v[16:31], v[64:67], v[76:79], v[16:31]
	ds_read_b128 v[104:107], v126 offset:32768
	v_mfma_f32_32x32x16_bf16 v[32:47], v[68:71], v[72:75], v[32:47]
	ds_read_b128 v[108:111], v126 offset:36864
	v_mfma_f32_32x32x16_bf16 v[0:15], v[68:71], v[76:79], v[0:15]
	ds_read_b128 v[100:103], v122 offset:36864
	s_waitcnt lgkmcnt(4)
	v_mfma_f32_32x32x16_bf16 v[48:63], v[80:83], v[88:91], v[48:63]
	ds_read_b128 v[64:67], v123 offset:32768
	v_mfma_f32_32x32x16_bf16 v[16:31], v[80:83], v[92:95], v[16:31]
	ds_read_b128 v[72:75], v127 offset:32768
	v_mfma_f32_32x32x16_bf16 v[32:47], v[84:87], v[88:91], v[32:47]
	ds_read_b128 v[76:79], v127 offset:36864
	v_mfma_f32_32x32x16_bf16 v[0:15], v[84:87], v[92:95], v[0:15]
	ds_read_b128 v[68:71], v123 offset:36864
	s_waitcnt lgkmcnt(4)
	v_mfma_f32_32x32x16_bf16 v[48:63], v[96:99], v[104:107], v[48:63]
	v_mfma_f32_32x32x16_bf16 v[16:31], v[96:99], v[108:111], v[16:31]
	v_mfma_f32_32x32x16_bf16 v[32:47], v[100:103], v[104:107], v[32:47]
	v_mfma_f32_32x32x16_bf16 v[0:15], v[100:103], v[108:111], v[0:15]
	s_waitcnt lgkmcnt(0)
	v_mfma_f32_32x32x16_bf16 v[48:63], v[64:67], v[72:75], v[48:63]
	v_mfma_f32_32x32x16_bf16 v[16:31], v[64:67], v[76:79], v[16:31]
	v_mfma_f32_32x32x16_bf16 v[32:47], v[68:71], v[72:75], v[32:47]
	v_mfma_f32_32x32x16_bf16 v[0:15], v[68:71], v[76:79], v[0:15]
	s_barrier
	s_add_u32 m0, s98, 0x8000
	s_nop 0
	global_load_lds_dwordx4 v112, s[6:7] offset:0
	global_load_lds_dwordx4 v113, s[6:7] offset:1024
	global_load_lds_dwordx4 v114, s[6:7] offset:2048
	global_load_lds_dwordx4 v115, s[6:7] offset:3072
	s_add_u32 m0, s98, 0x9000
	s_nop 0
	global_load_lds_dwordx4 v116, s[6:7] offset:0
	global_load_lds_dwordx4 v117, s[6:7] offset:1024
	global_load_lds_dwordx4 v118, s[6:7] offset:2048
	global_load_lds_dwordx4 v119, s[6:7] offset:3072
	s_add_u32 s6, s6, 0x80
	s_addc_u32 s7, s7, 0
	s_sub_u32 s8, s8, 1
	s_waitcnt vmcnt(8)
	s_cmp_lg_u32 s8, 0
	s_cbranch_scc1 .Lg4_loop
	s_barrier
	ds_read_b128 v[64:67], v120 offset:0
	ds_read_b128 v[72:75], v124 offset:0
	ds_read_b128 v[76:79], v124 offset:4096
	ds_read_b128 v[68:71], v120 offset:4096
	ds_read_b128 v[80:83], v121 offset:0
	ds_read_b128 v[88:91], v125 offset:0
	ds_read_b128 v[92:95], v125 offset:4096
	ds_read_b128 v[84:87], v121 offset:4096
	s_waitcnt lgkmcnt(4)
	v_mfma_f32_32x32x16_bf16 v[48:63], v[64:67], v[72:75], v[48:63]
	ds_read_b128 v[96:99], v122 offset:0
	v_mfma_f32_32x32x16_bf16 v[16:31], v[64:67], v[76:79], v[16:31]
	ds_read_b128 v[104:107], v126 offset:0
	v_mfma_f32_32x32x16_bf16 v[32:47], v[68:71], v[72:75], v[32:47]
	ds_read_b128 v[108:111], v126 offset:4096
	v_mfma_f32_32x32x16_bf16 v[0:15], v[68:71], v[76:79], v[0:15]
	ds_read_b128 v[100:103], v122 offset:4096
	s_waitcnt lgkmcnt(4)
	v_mfma_f32_32x32x16_bf16 v[48:63], v[80:83], v[88:91], v[48:63]
	ds_read_b128 v[64:67], v123 offset:0
	v_mfma_f32_32x32x16_bf16 v[16:31], v[80:83], v[92:95], v[16:31]
	ds_read_b128 v[72:75], v127 offset:0
	v_mfma_f32_32x32x16_bf16 v[32:47], v[84:87], v[88:91], v[32:47]
	ds_read_b128 v[76:79], v127 offset:4096
	v_mfma_f32_32x32x16_bf16 v[0:15], v[84:87], v[92:95], v[0:15]
	ds_read_b128 v[68:71], v123 offset:4096
	s_waitcnt lgkmcnt(4)
	v_mfma_f32_32x32x16_bf16 v[48:63], v[96:99], v[104:107], v[48:63]
	v_mfma_f32_32x32x16_bf16 v[16:31], v[96:99], v[108:111], v[16:31]
	v_mfma_f32_32x32x16_bf16 v[32:47], v[100:103], v[104:107], v[32:47]
	v_mfma_f32_32x32x16_bf16 v[0:15], v[100:103], v[108:111], v[0:15]
	s_waitcnt lgkmcnt(0)
	v_mfma_f32_32x32x16_bf16 v[48:63], v[64:67], v[72:75], v[48:63]
	v_mfma_f32_32x32x16_bf16 v[16:31], v[64:67], v[76:79], v[16:31]
	v_mfma_f32_32x32x16_bf16 v[32:47], v[68:71], v[72:75], v[32:47]
	v_mfma_f32_32x32x16_bf16 v[0:15], v[68:71], v[76:79], v[0:15]
	s_barrier
	s_add_i32 s99, s74, s92
	s_mov_b32 s8, 0
	s_cmp_gt_i32 s99, 0x8ff
	s_cbranch_scc1 .Lg4_nonext
	s_mul_hi_u32 s100, s99, 0xaaaaaaab
	s_lshr_b32 s100, s100, 6
	s_mul_i32 s101, s100, 0x60
	s_sub_u32 s101, s99, s101
	s_lshl_b32 s101, s101, 7
	s_lshl_b32 s100, s100, 7
	s_sub_i32 s101, s101, s11
	s_sub_i32 s100, s100, s10
	s_lshr_b32 s8, s98, 13
	s_cmp_lt_u32 s8, 2
	s_cselect_b32 s8, s101, s100
	s_mul_i32 s8, s8, 0x800
	s_sub_i32 s8, s8, 0x800
	s_ashr_i32 s101, s8, 31
	s_add_u32 s6, s6, s8
	s_addc_u32 s7, s7, s101
	s_add_u32 m0, s98, 0x0
	s_nop 0
	global_load_lds_dwordx4 v112, s[6:7] offset:0
	global_load_lds_dwordx4 v113, s[6:7] offset:1024
	global_load_lds_dwordx4 v114, s[6:7] offset:2048
	global_load_lds_dwordx4 v115, s[6:7] offset:3072
	s_add_u32 m0, s98, 0x1000
	s_nop 0
	global_load_lds_dwordx4 v116, s[6:7] offset:0
	global_load_lds_dwordx4 v117, s[6:7] offset:1024
	global_load_lds_dwordx4 v118, s[6:7] offset:2048
	global_load_lds_dwordx4 v119, s[6:7] offset:3072
	s_add_u32 s6, s6, 0x80
	s_addc_u32 s7, s7, 0
	s_mov_b32 s8, 1
.Lg4_nonext:
	s_cmp_lg_u32 s8, 0
	s_cbranch_scc1 .Lg4_w15p
	s_waitcnt vmcnt(0)
	s_branch .Lg4_s15

.Lg4_s15:
	s_barrier
	ds_read_b128 v[64:67], v120 offset:32768
	ds_read_b128 v[72:75], v124 offset:32768
	ds_read_b128 v[76:79], v124 offset:36864
	ds_read_b128 v[68:71], v120 offset:36864
	ds_read_b128 v[80:83], v121 offset:32768
	ds_read_b128 v[88:91], v125 offset:32768
	ds_read_b128 v[92:95], v125 offset:36864
	ds_read_b128 v[84:87], v121 offset:36864
	s_waitcnt lgkmcnt(4)
	v_mfma_f32_32x32x16_bf16 v[48:63], v[64:67], v[72:75], v[48:63]
	ds_read_b128 v[96:99], v122 offset:32768
	v_mfma_f32_32x32x16_bf16 v[16:31], v[64:67], v[76:79], v[16:31]
	ds_read_b128 v[104:107], v126 offset:32768
	v_mfma_f32_32x32x16_bf16 v[32:47], v[68:71], v[72:75], v[32:47]
	ds_read_b128 v[108:111], v126 offset:36864
	v_mfma_f32_32x32x16_bf16 v[0:15], v[68:71], v[76:79], v[0:15]
	ds_read_b128 v[100:103], v122 offset:36864
	s_waitcnt lgkmcnt(4)
	v_mfma_f32_32x32x16_bf16 v[48:63], v[80:83], v[88:91], v[48:63]
	ds_read_b128 v[64:67], v123 offset:32768
	v_mfma_f32_32x32x16_bf16 v[16:31], v[80:83], v[92:95], v[16:31]
	ds_read_b128 v[72:75], v127 offset:32768
	v_mfma_f32_32x32x16_bf16 v[32:47], v[84:87], v[88:91], v[32:47]
	ds_read_b128 v[76:79], v127 offset:36864
	v_mfma_f32_32x32x16_bf16 v[0:15], v[84:87], v[92:95], v[0:15]
	ds_read_b128 v[68:71], v123 offset:36864
	s_waitcnt lgkmcnt(4)
	v_mfma_f32_32x32x16_bf16 v[48:63], v[96:99], v[104:107], v[48:63]
	v_mfma_f32_32x32x16_bf16 v[16:31], v[96:99], v[108:111], v[16:31]
	v_mfma_f32_32x32x16_bf16 v[32:47], v[100:103], v[104:107], v[32:47]
	v_mfma_f32_32x32x16_bf16 v[0:15], v[100:103], v[108:111], v[0:15]
	s_waitcnt lgkmcnt(0)
	v_mfma_f32_32x32x16_bf16 v[48:63], v[64:67], v[72:75], v[48:63]
	v_mfma_f32_32x32x16_bf16 v[16:31], v[64:67], v[76:79], v[16:31]
	v_mfma_f32_32x32x16_bf16 v[32:47], v[68:71], v[72:75], v[32:47]
	v_mfma_f32_32x32x16_bf16 v[0:15], v[68:71], v[76:79], v[0:15]
	s_barrier
	v_writelane_b32 v251, s8, 0
	s_cmp_lg_u32 s8, 0
	s_cbranch_scc0 .Lg4_done
	s_add_u32 m0, s98, 0x8000
	s_nop 0
	global_load_lds_dwordx4 v112, s[6:7] offset:0
	global_load_lds_dwordx4 v113, s[6:7] offset:1024
	global_load_lds_dwordx4 v114, s[6:7] offset:2048
	global_load_lds_dwordx4 v115, s[6:7] offset:3072
	s_add_u32 m0, s98, 0x9000
	s_nop 0
	global_load_lds_dwordx4 v116, s[6:7] offset:0
	global_load_lds_dwordx4 v117, s[6:7] offset:1024
	global_load_lds_dwordx4 v118, s[6:7] offset:2048
	global_load_lds_dwordx4 v119, s[6:7] offset:3072
	s_add_u32 s6, s6, 0x80
	s_addc_u32 s7, s7, 0
.Lg4_done:
	s_nop 7
	s_nop 7
	s_branch .LBB0_1518
.LBB0_1518:
	s_lshr_b32 s12, s10, 10
	s_cmp_gt_u32 s12, 1
	s_cbranch_scc1 .Lodin4_old
	v_lshl_or_b32 v116, v183, 3, v191
	v_lshrrev_b32_e32 v117, 6, v116
	v_and_b32_e32 v118, 63, v116
	v_lshlrev_b32_e32 v113, 11, v117
	v_add_u32_e32 v113, 0x10000, v113
	v_readfirstlane_b32 s6, v117
	v_and_b32_e32 v116, 31, v118
	v_lshl_add_u32 v112, v116, 1, v113
	v_lshrrev_b32_e32 v117, 5, v118
	v_lshl_add_u32 v112, v117, 8, v112
	v_lshl_add_u32 v113, v118, 4, v113
	v_lshlrev_b32_e32 v115, 2, v116
	v_lshl_add_u32 v115, v117, 14, v115
	v_lshrrev_b32_e32 v117, 2, v118
	v_and_b32_e32 v114, 3, v118
	v_lshlrev_b32_e32 v114, 4, v114
	v_lshl_add_u32 v114, v117, 11, v114
	s_lshr_b32 s7, s6, 1
	s_lshl_b32 s7, s7, 6
	s_add_u32 s7, s7, s11
	s_and_b32 s6, s6, 1
	s_lshl_b32 s6, s6, 6
	s_and_b32 s8, s10, 0x3ff
	s_add_u32 s6, s6, s8
	s_cmp_eq_u32 s12, 2
	s_cbranch_scc1 .Lodin4_vseg
	s_cmp_ge_u32 s11, 0x2000
	s_cbranch_scc1 .Lodin4_rope
